# speedup vs baseline: 1.0000x; 1.0000x over previous
; __global__ void __launch_bounds__(256, 2) trunk_fwd(Params p) {
;     ...
;   if (phi > 1000) cg::this_grid().sync();
.LBB0_14:
	s_sleep 3
	global_load_dword v2, v0, s[2:3] offset:32 sc1
	s_waitcnt vmcnt(0)
	v_and_b32_e32 v2, 0xffff0000, v2
	v_cmp_ne_u32_e32 vcc, v2, v1
	s_or_b64 s[4:5], vcc, s[4:5]
	s_andn2_b64 exec, exec, s[4:5]
	s_cbranch_execnz .LBB0_14

; DI unsigned xb_ld(unsigned* p) { return __hip_atomic_load(p, __ATOMIC_RELAXED, __HIP_MEMORY_SCOPE_AGENT); }
; DI void xcd_barrier_complete(unsigned* bar, unsigned x, unsigned& nloc, unsigned& nx) {
;     ...
;   for (;;) {
;     sum = 0u; cnt = 0u; mine = 0u;
; #pragma unroll
;     for (unsigned j = 0; j < 16; ++j) { const unsigned c = xb_ld(&bar[XB_XCNT(j)]); sum += c; cnt += (c > 0u) ? 1u : 0u; mine = (j == x) ? c : mine; }
;     if (sum == G) break;
;     __builtin_amdgcn_s_sleep(1);
;     if ((++sp & 255u) == 0u) { if (xb_ld(&bar[XB_TMO])) break; if (sp > XB_SPIN_CAP) { atomicAdd(&bar[XB_TMO], 1u); break; } }
;   }
.LBB0_23:
	global_load_dword v15, v16, s[44:45] offset:1024 sc1
	global_load_dword v0, v16, s[44:45] offset:1280 sc1
	global_load_dword v1, v16, s[44:45] offset:1536 sc1
	global_load_dword v2, v16, s[44:45] offset:1792 sc1
	global_load_dword v3, v16, s[44:45] offset:2048 sc1
	global_load_dword v4, v16, s[44:45] offset:2304 sc1
	global_load_dword v5, v16, s[44:45] offset:2560 sc1
	global_load_dword v6, v16, s[44:45] offset:2816 sc1
	global_load_dword v7, v16, s[44:45] offset:3072 sc1
	global_load_dword v8, v16, s[44:45] offset:3328 sc1
	global_load_dword v9, v16, s[44:45] offset:3584 sc1
	global_load_dword v10, v16, s[44:45] offset:3840 sc1
	global_load_dword v11, v16, s[0:1] sc1
	global_load_dword v12, v16, s[6:7] sc1
	global_load_dword v13, v16, s[8:9] sc1
	global_load_dword v14, v16, s[10:11] sc1
	s_mov_b64 s[12:13], -1
	s_mov_b64 s[14:15], -1
	s_waitcnt vmcnt(14)
	v_add_u32_e32 v17, v0, v15
	s_waitcnt vmcnt(13)
	v_add_u32_e32 v17, v17, v1
	s_waitcnt vmcnt(12)
	v_add_u32_e32 v17, v17, v2
	s_waitcnt vmcnt(11)
	v_add_u32_e32 v17, v17, v3
	s_waitcnt vmcnt(10)
	v_add_u32_e32 v17, v17, v4
	s_waitcnt vmcnt(9)
	v_add_u32_e32 v17, v17, v5
	s_waitcnt vmcnt(8)
	v_add_u32_e32 v17, v17, v6
	s_waitcnt vmcnt(7)
	v_add_u32_e32 v17, v17, v7
	s_waitcnt vmcnt(6)
	v_add_u32_e32 v17, v17, v8
	s_waitcnt vmcnt(5)
	v_add_u32_e32 v17, v17, v9
	s_waitcnt vmcnt(4)
	v_add_u32_e32 v17, v17, v10
	s_waitcnt vmcnt(3)
	v_add_u32_e32 v17, v17, v11
	s_waitcnt vmcnt(2)
	v_add_u32_e32 v17, v17, v12
	s_waitcnt vmcnt(1)
	v_add_u32_e32 v17, v17, v13
	s_waitcnt vmcnt(0)
	v_add_u32_e32 v17, v17, v14
	v_cmp_eq_u32_e32 vcc, s18, v17
	s_cbranch_vccnz .LBB0_22
	s_and_b32 s12, s19, 0xff
	s_cmp_eq_u32 s12, 0
	s_mov_b64 s[12:13], -1
	s_mov_b64 s[16:17], -1
	s_sleep 3
	s_cbranch_scc0 .LBB0_27
	global_load_dword v17, v16, s[44:45] offset:512 sc1
	s_waitcnt vmcnt(0)
	v_cmp_eq_u32_e32 vcc, 0, v17
	s_cbranch_vccnz .LBB0_29
	s_mov_b64 s[16:17], 0

; DI unsigned xb_ld(unsigned* p) { return __hip_atomic_load(p, __ATOMIC_RELAXED, __HIP_MEMORY_SCOPE_AGENT); }
; DI unsigned xb_add(unsigned* p, unsigned v) { return __hip_atomic_fetch_add(p, v, __ATOMIC_RELAXED, __HIP_MEMORY_SCOPE_AGENT); }
; #define XB_SPIN(cond, bar) do { unsigned _sp = 0; while (cond) { __builtin_amdgcn_s_sleep(1); \
;     if ((++_sp & 255u) == 0u) { if (xb_ld(&(bar)[XB_TMO])) break; if (_sp > XB_SPIN_CAP) { atomicAdd(&(bar)[XB_TMO], 1u); break; } } } } while (0)
; DI void xcd_barrier(const XcdBarrier& b) {
;     ...
;       else XB_SPIN(xb_ld(&bar[XB_TOPGEN]) == tg, bar);
;       __builtin_amdgcn_fence(__ATOMIC_ACQUIRE, "agent");
;       xb_add(&bar[XB_XGEN(b.x)], 1u);
;       asm volatile("s_waitcnt vmcnt(0)" ::: "memory");
;     } else {
;       XB_SPIN(xb_ld(&bar[XB_XGEN(b.x)]) == gen, bar);
.LBB0_41:
	s_and_b32 s18, s22, 0xff
	s_mov_b64 s[16:17], -1
	s_cmp_lg_u32 s18, 0
	s_mov_b64 s[20:21], -1
	s_sleep 3
	s_cbranch_scc1 .LBB0_44
	global_load_dword v2, v0, s[44:45] offset:512 sc1
	s_waitcnt vmcnt(0)
	v_cmp_eq_u32_e32 vcc, 0, v2
	s_cbranch_vccnz .LBB0_46
	s_mov_b64 s[20:21], 0
	s_mov_b64 s[18:19], -1

; DI unsigned xb_ld(unsigned* p) { return __hip_atomic_load(p, __ATOMIC_RELAXED, __HIP_MEMORY_SCOPE_AGENT); }
; DI unsigned xb_add(unsigned* p, unsigned v) { return __hip_atomic_fetch_add(p, v, __ATOMIC_RELAXED, __HIP_MEMORY_SCOPE_AGENT); }
; #define XB_SPIN(cond, bar) do { unsigned _sp = 0; while (cond) { __builtin_amdgcn_s_sleep(1); \
;     if ((++_sp & 255u) == 0u) { if (xb_ld(&(bar)[XB_TMO])) break; if (_sp > XB_SPIN_CAP) { atomicAdd(&(bar)[XB_TMO], 1u); break; } } } } while (0)
; DI void xcd_barrier(const XcdBarrier& b) {
;     ...
;       else XB_SPIN(xb_ld(&bar[XB_TOPGEN]) == tg, bar);
;       __builtin_amdgcn_fence(__ATOMIC_ACQUIRE, "agent");
;       xb_add(&bar[XB_XGEN(b.x)], 1u);
;       asm volatile("s_waitcnt vmcnt(0)" ::: "memory");
;     } else {
;       XB_SPIN(xb_ld(&bar[XB_XGEN(b.x)]) == gen, bar);
.LBB0_58:
	s_and_b32 s18, s24, 0xff
	s_cmp_lg_u32 s18, 0
	s_mov_b64 s[20:21], -1
	s_sleep 3
	s_cbranch_scc1 .LBB0_61
	global_load_dword v1, v0, s[10:11] sc1
	s_waitcnt vmcnt(0)
	v_cmp_eq_u32_e32 vcc, 0, v1
	s_cbranch_vccnz .LBB0_63
	s_mov_b64 s[20:21], 0
	s_mov_b64 s[18:19], -1

; DI unsigned xb_ld(unsigned* p) { return __hip_atomic_load(p, __ATOMIC_RELAXED, __HIP_MEMORY_SCOPE_AGENT); }
; DI void xcd_barrier_complete(unsigned* bar, unsigned x, unsigned& nloc, unsigned& nx) {
;     ...
;   for (;;) {
;     sum = 0u; cnt = 0u; mine = 0u;
; #pragma unroll
;     for (unsigned j = 0; j < 16; ++j) { const unsigned c = xb_ld(&bar[XB_XCNT(j)]); sum += c; cnt += (c > 0u) ? 1u : 0u; mine = (j == x) ? c : mine; }
;     if (sum == G) break;
;     __builtin_amdgcn_s_sleep(1);
;     if ((++sp & 255u) == 0u) { if (xb_ld(&bar[XB_TMO])) break; if (sp > XB_SPIN_CAP) { atomicAdd(&bar[XB_TMO], 1u); break; } }
;   }
.LBB0_162:
	global_load_dword v15, v16, s[44:45] offset:1024 sc1
	global_load_dword v0, v16, s[44:45] offset:1280 sc1
	global_load_dword v1, v16, s[44:45] offset:1536 sc1
	global_load_dword v2, v16, s[44:45] offset:1792 sc1
	global_load_dword v3, v16, s[44:45] offset:2048 sc1
	global_load_dword v4, v16, s[44:45] offset:2304 sc1
	global_load_dword v5, v16, s[44:45] offset:2560 sc1
	global_load_dword v6, v16, s[44:45] offset:2816 sc1
	global_load_dword v7, v16, s[44:45] offset:3072 sc1
	global_load_dword v8, v16, s[44:45] offset:3328 sc1
	global_load_dword v9, v16, s[44:45] offset:3584 sc1
	global_load_dword v10, v16, s[44:45] offset:3840 sc1
	global_load_dword v11, v16, s[0:1] sc1
	global_load_dword v12, v16, s[4:5] sc1
	global_load_dword v13, v16, s[6:7] sc1
	global_load_dword v14, v16, s[8:9] sc1
	s_mov_b64 s[10:11], -1
	s_mov_b64 s[12:13], -1
	s_waitcnt vmcnt(14)
	v_add_u32_e32 v17, v0, v15
	s_waitcnt vmcnt(13)
	v_add_u32_e32 v17, v17, v1
	s_waitcnt vmcnt(12)
	v_add_u32_e32 v17, v17, v2
	s_waitcnt vmcnt(11)
	v_add_u32_e32 v17, v17, v3
	s_waitcnt vmcnt(10)
	v_add_u32_e32 v17, v17, v4
	s_waitcnt vmcnt(9)
	v_add_u32_e32 v17, v17, v5
	s_waitcnt vmcnt(8)
	v_add_u32_e32 v17, v17, v6
	s_waitcnt vmcnt(7)
	v_add_u32_e32 v17, v17, v7
	s_waitcnt vmcnt(6)
	v_add_u32_e32 v17, v17, v8
	s_waitcnt vmcnt(5)
	v_add_u32_e32 v17, v17, v9
	s_waitcnt vmcnt(4)
	v_add_u32_e32 v17, v17, v10
	s_waitcnt vmcnt(3)
	v_add_u32_e32 v17, v17, v11
	s_waitcnt vmcnt(2)
	v_add_u32_e32 v17, v17, v12
	s_waitcnt vmcnt(1)
	v_add_u32_e32 v17, v17, v13
	s_waitcnt vmcnt(0)
	v_add_u32_e32 v17, v17, v14
	v_cmp_eq_u32_e32 vcc, s18, v17
	s_cbranch_vccnz .LBB0_161
	s_and_b32 s10, s19, 0xff
	s_cmp_eq_u32 s10, 0
	s_mov_b64 s[10:11], -1
	s_mov_b64 s[16:17], -1
	s_sleep 3
	s_cbranch_scc0 .LBB0_166
	global_load_dword v17, v16, s[44:45] offset:512 sc1
	s_waitcnt vmcnt(0)
	v_cmp_eq_u32_e32 vcc, 0, v17
	s_cbranch_vccnz .LBB0_168
	s_mov_b64 s[16:17], 0

; DI unsigned xb_ld(unsigned* p) { return __hip_atomic_load(p, __ATOMIC_RELAXED, __HIP_MEMORY_SCOPE_AGENT); }
; DI unsigned xb_add(unsigned* p, unsigned v) { return __hip_atomic_fetch_add(p, v, __ATOMIC_RELAXED, __HIP_MEMORY_SCOPE_AGENT); }
; #define XB_SPIN(cond, bar) do { unsigned _sp = 0; while (cond) { __builtin_amdgcn_s_sleep(1); \
;     if ((++_sp & 255u) == 0u) { if (xb_ld(&(bar)[XB_TMO])) break; if (_sp > XB_SPIN_CAP) { atomicAdd(&(bar)[XB_TMO], 1u); break; } } } } while (0)
; DI void xcd_barrier(const XcdBarrier& b) {
;     ...
;       else XB_SPIN(xb_ld(&bar[XB_TOPGEN]) == tg, bar);
;       __builtin_amdgcn_fence(__ATOMIC_ACQUIRE, "agent");
;       xb_add(&bar[XB_XGEN(b.x)], 1u);
;       asm volatile("s_waitcnt vmcnt(0)" ::: "memory");
;     } else {
;       XB_SPIN(xb_ld(&bar[XB_XGEN(b.x)]) == gen, bar);
.LBB0_197:
	s_and_b32 s18, s24, 0xff
	s_cmp_lg_u32 s18, 0
	s_mov_b64 s[20:21], -1
	s_sleep 3
	s_cbranch_scc1 .LBB0_200
	global_load_dword v1, v0, s[8:9] sc1
	s_waitcnt vmcnt(0)
	v_cmp_eq_u32_e32 vcc, 0, v1
	s_cbranch_vccnz .LBB0_202
	s_mov_b64 s[20:21], 0
	s_mov_b64 s[18:19], -1

; DI unsigned xb_ld(unsigned* p) { return __hip_atomic_load(p, __ATOMIC_RELAXED, __HIP_MEMORY_SCOPE_AGENT); }
; DI void xcd_barrier_complete(unsigned* bar, unsigned x, unsigned& nloc, unsigned& nx) {
;     ...
;   for (;;) {
;     sum = 0u; cnt = 0u; mine = 0u;
; #pragma unroll
;     for (unsigned j = 0; j < 16; ++j) { const unsigned c = xb_ld(&bar[XB_XCNT(j)]); sum += c; cnt += (c > 0u) ? 1u : 0u; mine = (j == x) ? c : mine; }
;     if (sum == G) break;
;     __builtin_amdgcn_s_sleep(1);
;     if ((++sp & 255u) == 0u) { if (xb_ld(&bar[XB_TMO])) break; if (sp > XB_SPIN_CAP) { atomicAdd(&bar[XB_TMO], 1u); break; } }
;   }
.LBB0_686:
	global_load_dword v15, v16, s[44:45] offset:1024 sc1
	global_load_dword v0, v16, s[44:45] offset:1280 sc1
	global_load_dword v1, v16, s[44:45] offset:1536 sc1
	global_load_dword v2, v16, s[44:45] offset:1792 sc1
	global_load_dword v3, v16, s[44:45] offset:2048 sc1
	global_load_dword v4, v16, s[44:45] offset:2304 sc1
	global_load_dword v5, v16, s[44:45] offset:2560 sc1
	global_load_dword v6, v16, s[44:45] offset:2816 sc1
	global_load_dword v7, v16, s[44:45] offset:3072 sc1
	global_load_dword v8, v16, s[44:45] offset:3328 sc1
	global_load_dword v9, v16, s[44:45] offset:3584 sc1
	global_load_dword v10, v16, s[44:45] offset:3840 sc1
	global_load_dword v11, v16, s[0:1] sc1
	global_load_dword v12, v16, s[4:5] sc1
	global_load_dword v13, v16, s[6:7] sc1
	global_load_dword v14, v16, s[10:11] sc1
	s_mov_b64 s[12:13], -1
	s_mov_b64 s[14:15], -1
	s_waitcnt vmcnt(14)
	v_add_u32_e32 v17, v0, v15
	s_waitcnt vmcnt(13)
	v_add_u32_e32 v17, v17, v1
	s_waitcnt vmcnt(12)
	v_add_u32_e32 v17, v17, v2
	s_waitcnt vmcnt(11)
	v_add_u32_e32 v17, v17, v3
	s_waitcnt vmcnt(10)
	v_add_u32_e32 v17, v17, v4
	s_waitcnt vmcnt(9)
	v_add_u32_e32 v17, v17, v5
	s_waitcnt vmcnt(8)
	v_add_u32_e32 v17, v17, v6
	s_waitcnt vmcnt(7)
	v_add_u32_e32 v17, v17, v7
	s_waitcnt vmcnt(6)
	v_add_u32_e32 v17, v17, v8
	s_waitcnt vmcnt(5)
	v_add_u32_e32 v17, v17, v9
	s_waitcnt vmcnt(4)
	v_add_u32_e32 v17, v17, v10
	s_waitcnt vmcnt(3)
	v_add_u32_e32 v17, v17, v11
	s_waitcnt vmcnt(2)
	v_add_u32_e32 v17, v17, v12
	s_waitcnt vmcnt(1)
	v_add_u32_e32 v17, v17, v13
	s_waitcnt vmcnt(0)
	v_add_u32_e32 v17, v17, v14
	v_cmp_eq_u32_e32 vcc, s18, v17
	s_cbranch_vccnz .LBB0_685
	s_and_b32 s12, s19, 0xff
	s_cmp_eq_u32 s12, 0
	s_mov_b64 s[12:13], -1
	s_mov_b64 s[16:17], -1
	s_sleep 3
	s_cbranch_scc0 .LBB0_690
	global_load_dword v17, v16, s[44:45] offset:512 sc1
	s_waitcnt vmcnt(0)
	v_cmp_eq_u32_e32 vcc, 0, v17
	s_cbranch_vccnz .LBB0_692
	s_mov_b64 s[16:17], 0

; DI unsigned xb_ld(unsigned* p) { return __hip_atomic_load(p, __ATOMIC_RELAXED, __HIP_MEMORY_SCOPE_AGENT); }
; DI void xcd_barrier_complete(unsigned* bar, unsigned x, unsigned& nloc, unsigned& nx) {
;     ...
;   for (;;) {
;     sum = 0u; cnt = 0u; mine = 0u;
; #pragma unroll
;     for (unsigned j = 0; j < 16; ++j) { const unsigned c = xb_ld(&bar[XB_XCNT(j)]); sum += c; cnt += (c > 0u) ? 1u : 0u; mine = (j == x) ? c : mine; }
;     if (sum == G) break;
;     __builtin_amdgcn_s_sleep(1);
;     if ((++sp & 255u) == 0u) { if (xb_ld(&bar[XB_TMO])) break; if (sp > XB_SPIN_CAP) { atomicAdd(&bar[XB_TMO], 1u); break; } }
;   }
.LBB0_750:
	global_load_dword v15, v16, s[44:45] offset:1024 sc1
	global_load_dword v0, v16, s[44:45] offset:1280 sc1
	global_load_dword v1, v16, s[44:45] offset:1536 sc1
	global_load_dword v2, v16, s[44:45] offset:1792 sc1
	global_load_dword v3, v16, s[44:45] offset:2048 sc1
	global_load_dword v4, v16, s[44:45] offset:2304 sc1
	global_load_dword v5, v16, s[44:45] offset:2560 sc1
	global_load_dword v6, v16, s[44:45] offset:2816 sc1
	global_load_dword v7, v16, s[44:45] offset:3072 sc1
	global_load_dword v8, v16, s[44:45] offset:3328 sc1
	global_load_dword v9, v16, s[44:45] offset:3584 sc1
	global_load_dword v10, v16, s[44:45] offset:3840 sc1
	global_load_dword v11, v16, s[0:1] sc1
	global_load_dword v12, v16, s[4:5] sc1
	global_load_dword v13, v16, s[6:7] sc1
	global_load_dword v14, v16, s[8:9] sc1
	s_mov_b64 s[10:11], -1
	s_mov_b64 s[12:13], -1
	s_waitcnt vmcnt(14)
	v_add_u32_e32 v17, v0, v15
	s_waitcnt vmcnt(13)
	v_add_u32_e32 v17, v17, v1
	s_waitcnt vmcnt(12)
	v_add_u32_e32 v17, v17, v2
	s_waitcnt vmcnt(11)
	v_add_u32_e32 v17, v17, v3
	s_waitcnt vmcnt(10)
	v_add_u32_e32 v17, v17, v4
	s_waitcnt vmcnt(9)
	v_add_u32_e32 v17, v17, v5
	s_waitcnt vmcnt(8)
	v_add_u32_e32 v17, v17, v6
	s_waitcnt vmcnt(7)
	v_add_u32_e32 v17, v17, v7
	s_waitcnt vmcnt(6)
	v_add_u32_e32 v17, v17, v8
	s_waitcnt vmcnt(5)
	v_add_u32_e32 v17, v17, v9
	s_waitcnt vmcnt(4)
	v_add_u32_e32 v17, v17, v10
	s_waitcnt vmcnt(3)
	v_add_u32_e32 v17, v17, v11
	s_waitcnt vmcnt(2)
	v_add_u32_e32 v17, v17, v12
	s_waitcnt vmcnt(1)
	v_add_u32_e32 v17, v17, v13
	s_waitcnt vmcnt(0)
	v_add_u32_e32 v17, v17, v14
	v_cmp_eq_u32_e32 vcc, s16, v17
	s_cbranch_vccnz .LBB0_749
	s_and_b32 s10, s17, 0xff
	s_cmp_eq_u32 s10, 0
	s_mov_b64 s[10:11], -1
	s_mov_b64 s[14:15], -1
	s_sleep 3
	s_cbranch_scc0 .LBB0_754
	global_load_dword v17, v16, s[44:45] offset:512 sc1
	s_waitcnt vmcnt(0)
	v_cmp_eq_u32_e32 vcc, 0, v17
	s_cbranch_vccnz .LBB0_756
	s_mov_b64 s[14:15], 0

; DI unsigned xb_ld(unsigned* p) { return __hip_atomic_load(p, __ATOMIC_RELAXED, __HIP_MEMORY_SCOPE_AGENT); }
; DI unsigned xb_add(unsigned* p, unsigned v) { return __hip_atomic_fetch_add(p, v, __ATOMIC_RELAXED, __HIP_MEMORY_SCOPE_AGENT); }
; #define XB_SPIN(cond, bar) do { unsigned _sp = 0; while (cond) { __builtin_amdgcn_s_sleep(1); \
;     if ((++_sp & 255u) == 0u) { if (xb_ld(&(bar)[XB_TMO])) break; if (_sp > XB_SPIN_CAP) { atomicAdd(&(bar)[XB_TMO], 1u); break; } } } } while (0)
; DI void xcd_barrier(const XcdBarrier& b) {
;     ...
;       else XB_SPIN(xb_ld(&bar[XB_TOPGEN]) == tg, bar);
;       __builtin_amdgcn_fence(__ATOMIC_ACQUIRE, "agent");
;       xb_add(&bar[XB_XGEN(b.x)], 1u);
;       asm volatile("s_waitcnt vmcnt(0)" ::: "memory");
;     } else {
;       XB_SPIN(xb_ld(&bar[XB_XGEN(b.x)]) == gen, bar);
.LBB0_768:
	s_and_b32 s16, s20, 0xff
	s_mov_b64 s[14:15], -1
	s_cmp_lg_u32 s16, 0
	s_mov_b64 s[18:19], -1
	s_sleep 3
	s_cbranch_scc1 .LBB0_771
	global_load_dword v2, v0, s[44:45] offset:512 sc1
	s_waitcnt vmcnt(0)
	v_cmp_eq_u32_e32 vcc, 0, v2
	s_cbranch_vccnz .LBB0_773
	s_mov_b64 s[18:19], 0
	s_mov_b64 s[16:17], -1

; DI unsigned xb_ld(unsigned* p) { return __hip_atomic_load(p, __ATOMIC_RELAXED, __HIP_MEMORY_SCOPE_AGENT); }
; DI unsigned xb_add(unsigned* p, unsigned v) { return __hip_atomic_fetch_add(p, v, __ATOMIC_RELAXED, __HIP_MEMORY_SCOPE_AGENT); }
; #define XB_SPIN(cond, bar) do { unsigned _sp = 0; while (cond) { __builtin_amdgcn_s_sleep(1); \
;     if ((++_sp & 255u) == 0u) { if (xb_ld(&(bar)[XB_TMO])) break; if (_sp > XB_SPIN_CAP) { atomicAdd(&(bar)[XB_TMO], 1u); break; } } } } while (0)
; DI void xcd_barrier(const XcdBarrier& b) {
;     ...
;       else XB_SPIN(xb_ld(&bar[XB_TOPGEN]) == tg, bar);
;       __builtin_amdgcn_fence(__ATOMIC_ACQUIRE, "agent");
;       xb_add(&bar[XB_XGEN(b.x)], 1u);
;       asm volatile("s_waitcnt vmcnt(0)" ::: "memory");
;     } else {
;       XB_SPIN(xb_ld(&bar[XB_XGEN(b.x)]) == gen, bar);
.LBB0_785:
	s_and_b32 s16, s22, 0xff
	s_cmp_lg_u32 s16, 0
	s_mov_b64 s[18:19], -1
	s_sleep 3
	s_cbranch_scc1 .LBB0_788
	global_load_dword v1, v0, s[8:9] sc1
	s_waitcnt vmcnt(0)
	v_cmp_eq_u32_e32 vcc, 0, v1
	s_cbranch_vccnz .LBB0_790
	s_mov_b64 s[18:19], 0
	s_mov_b64 s[16:17], -1

; DI unsigned xb_ld(unsigned* p) { return __hip_atomic_load(p, __ATOMIC_RELAXED, __HIP_MEMORY_SCOPE_AGENT); }
; DI unsigned xb_add(unsigned* p, unsigned v) { return __hip_atomic_fetch_add(p, v, __ATOMIC_RELAXED, __HIP_MEMORY_SCOPE_AGENT); }
; #define XB_SPIN(cond, bar) do { unsigned _sp = 0; while (cond) { __builtin_amdgcn_s_sleep(1); \
;     if ((++_sp & 255u) == 0u) { if (xb_ld(&(bar)[XB_TMO])) break; if (_sp > XB_SPIN_CAP) { atomicAdd(&(bar)[XB_TMO], 1u); break; } } } } while (0)
; DI void xcd_barrier(const XcdBarrier& b) {
;     ...
;       else XB_SPIN(xb_ld(&bar[XB_TOPGEN]) == tg, bar);
;       __builtin_amdgcn_fence(__ATOMIC_ACQUIRE, "agent");
;       xb_add(&bar[XB_XGEN(b.x)], 1u);
;       asm volatile("s_waitcnt vmcnt(0)" ::: "memory");
;     } else {
;       XB_SPIN(xb_ld(&bar[XB_XGEN(b.x)]) == gen, bar);
.LBB0_1088:
	s_and_b32 s16, s24, 0xff
	s_cmp_lg_u32 s16, 0
	s_mov_b64 s[18:19], -1
	s_sleep 3
	s_cbranch_scc1 .LBB0_1091
	global_load_dword v1, v0, s[8:9] sc1
	s_waitcnt vmcnt(0)
	v_cmp_eq_u32_e32 vcc, 0, v1
	s_cbranch_vccnz .LBB0_1093
	s_mov_b64 s[18:19], 0
	s_mov_b64 s[16:17], -1

; DI void diff_attn_phase(const Params& p, char* smem) {
;     ...
;     if (tid == 0) {
;       unsigned sp = 0;
;       while (__hip_atomic_load(p.pflag + pair, __ATOMIC_RELAXED, __HIP_MEMORY_SCOPE_AGENT) == 0u) { __builtin_amdgcn_s_sleep(2); if (++sp > (1u << 26)) break; }
;       __builtin_amdgcn_fence(__ATOMIC_ACQUIRE, "agent");
;       asm volatile("s_waitcnt vmcnt(0)" ::: "memory");
;     }
.LBB0_1505:
	global_load_dword v0, v1, s[4:5] sc1
	s_mov_b64 s[6:7], -1
	s_waitcnt vmcnt(0)
	v_cmp_ne_u32_e32 vcc, 0, v0
	s_cbranch_vccnz .LBB0_1504
	s_sleep 3
	global_load_dword v0, v1, s[4:5] sc1
	s_waitcnt vmcnt(0)
	v_cmp_eq_u32_e32 vcc, 0, v0
	s_cbranch_vccz .LBB0_1504
	s_sleep 3
	global_load_dword v0, v1, s[4:5] sc1
	s_waitcnt vmcnt(0)
	v_cmp_eq_u32_e32 vcc, 0, v0
	s_cbranch_vccz .LBB0_1504
	s_sleep 3
	global_load_dword v0, v1, s[4:5] sc1
	s_waitcnt vmcnt(0)
	v_cmp_eq_u32_e32 vcc, 0, v0
	s_cbranch_vccz .LBB0_1504
	s_sleep 3
	global_load_dword v0, v1, s[4:5] sc1
	s_waitcnt vmcnt(0)
	v_cmp_eq_u32_e32 vcc, 0, v0
	s_cbranch_vccz .LBB0_1504
	s_add_i32 s8, s8, -5
	s_cmp_eq_u32 s8, 0
	s_cselect_b64 s[6:7], -1, 0
	s_sleep 3
	s_branch .LBB0_1504

; DI unsigned xb_ld(unsigned* p) { return __hip_atomic_load(p, __ATOMIC_RELAXED, __HIP_MEMORY_SCOPE_AGENT); }
; DI void xcd_barrier_complete(unsigned* bar, unsigned x, unsigned& nloc, unsigned& nx) {
;     ...
;   for (;;) {
;     sum = 0u; cnt = 0u; mine = 0u;
; #pragma unroll
;     for (unsigned j = 0; j < 16; ++j) { const unsigned c = xb_ld(&bar[XB_XCNT(j)]); sum += c; cnt += (c > 0u) ? 1u : 0u; mine = (j == x) ? c : mine; }
;     if (sum == G) break;
;     __builtin_amdgcn_s_sleep(1);
;     if ((++sp & 255u) == 0u) { if (xb_ld(&bar[XB_TMO])) break; if (sp > XB_SPIN_CAP) { atomicAdd(&bar[XB_TMO], 1u); break; } }
;   }
.LBB0_1648:
	global_load_dword v15, v16, s[44:45] offset:1024 sc1
	global_load_dword v0, v16, s[44:45] offset:1280 sc1
	global_load_dword v1, v16, s[44:45] offset:1536 sc1
	global_load_dword v2, v16, s[44:45] offset:1792 sc1
	global_load_dword v3, v16, s[44:45] offset:2048 sc1
	global_load_dword v4, v16, s[44:45] offset:2304 sc1
	global_load_dword v5, v16, s[44:45] offset:2560 sc1
	global_load_dword v6, v16, s[44:45] offset:2816 sc1
	global_load_dword v7, v16, s[44:45] offset:3072 sc1
	global_load_dword v8, v16, s[44:45] offset:3328 sc1
	global_load_dword v9, v16, s[44:45] offset:3584 sc1
	global_load_dword v10, v16, s[44:45] offset:3840 sc1
	global_load_dword v11, v16, s[0:1] sc1
	global_load_dword v12, v16, s[4:5] sc1
	global_load_dword v13, v16, s[6:7] sc1
	global_load_dword v14, v16, s[8:9] sc1
	s_mov_b64 s[10:11], -1
	s_mov_b64 s[12:13], -1
	s_waitcnt vmcnt(14)
	v_add_u32_e32 v17, v0, v15
	s_waitcnt vmcnt(13)
	v_add_u32_e32 v17, v17, v1
	s_waitcnt vmcnt(12)
	v_add_u32_e32 v17, v17, v2
	s_waitcnt vmcnt(11)
	v_add_u32_e32 v17, v17, v3
	s_waitcnt vmcnt(10)
	v_add_u32_e32 v17, v17, v4
	s_waitcnt vmcnt(9)
	v_add_u32_e32 v17, v17, v5
	s_waitcnt vmcnt(8)
	v_add_u32_e32 v17, v17, v6
	s_waitcnt vmcnt(7)
	v_add_u32_e32 v17, v17, v7
	s_waitcnt vmcnt(6)
	v_add_u32_e32 v17, v17, v8
	s_waitcnt vmcnt(5)
	v_add_u32_e32 v17, v17, v9
	s_waitcnt vmcnt(4)
	v_add_u32_e32 v17, v17, v10
	s_waitcnt vmcnt(3)
	v_add_u32_e32 v17, v17, v11
	s_waitcnt vmcnt(2)
	v_add_u32_e32 v17, v17, v12
	s_waitcnt vmcnt(1)
	v_add_u32_e32 v17, v17, v13
	s_waitcnt vmcnt(0)
	v_add_u32_e32 v17, v17, v14
	v_cmp_eq_u32_e32 vcc, s18, v17
	s_cbranch_vccnz .LBB0_1647
	s_and_b32 s10, s19, 0xff
	s_cmp_eq_u32 s10, 0
	s_mov_b64 s[10:11], -1
	s_mov_b64 s[14:15], -1
	s_sleep 3
	s_cbranch_scc0 .LBB0_1652
	global_load_dword v17, v16, s[44:45] offset:512 sc1
	s_waitcnt vmcnt(0)
	v_cmp_eq_u32_e32 vcc, 0, v17
	s_cbranch_vccnz .LBB0_1654
	s_mov_b64 s[14:15], 0

; DI unsigned xb_ld(unsigned* p) { return __hip_atomic_load(p, __ATOMIC_RELAXED, __HIP_MEMORY_SCOPE_AGENT); }
; DI unsigned xb_add(unsigned* p, unsigned v) { return __hip_atomic_fetch_add(p, v, __ATOMIC_RELAXED, __HIP_MEMORY_SCOPE_AGENT); }
; #define XB_SPIN(cond, bar) do { unsigned _sp = 0; while (cond) { __builtin_amdgcn_s_sleep(1); \
;     if ((++_sp & 255u) == 0u) { if (xb_ld(&(bar)[XB_TMO])) break; if (_sp > XB_SPIN_CAP) { atomicAdd(&(bar)[XB_TMO], 1u); break; } } } } while (0)
; DI void xcd_barrier(const XcdBarrier& b) {
;     ...
;       else XB_SPIN(xb_ld(&bar[XB_TOPGEN]) == tg, bar);
;       __builtin_amdgcn_fence(__ATOMIC_ACQUIRE, "agent");
;       xb_add(&bar[XB_XGEN(b.x)], 1u);
;       asm volatile("s_waitcnt vmcnt(0)" ::: "memory");
;     } else {
;       XB_SPIN(xb_ld(&bar[XB_XGEN(b.x)]) == gen, bar);
.LBB0_1666:
	s_and_b32 s18, s22, 0xff
	s_mov_b64 s[14:15], -1
	s_cmp_lg_u32 s18, 0
	s_mov_b64 s[20:21], -1
	s_sleep 3
	s_cbranch_scc1 .LBB0_1669
	global_load_dword v2, v0, s[44:45] offset:512 sc1
	s_waitcnt vmcnt(0)
	v_cmp_eq_u32_e32 vcc, 0, v2
	s_cbranch_vccnz .LBB0_1671
	s_mov_b64 s[20:21], 0
	s_mov_b64 s[18:19], -1

; DI unsigned xb_ld(unsigned* p) { return __hip_atomic_load(p, __ATOMIC_RELAXED, __HIP_MEMORY_SCOPE_AGENT); }
; DI void xcd_barrier_complete(unsigned* bar, unsigned x, unsigned& nloc, unsigned& nx) {
;     ...
;   for (;;) {
;     sum = 0u; cnt = 0u; mine = 0u;
; #pragma unroll
;     for (unsigned j = 0; j < 16; ++j) { const unsigned c = xb_ld(&bar[XB_XCNT(j)]); sum += c; cnt += (c > 0u) ? 1u : 0u; mine = (j == x) ? c : mine; }
;     if (sum == G) break;
;     __builtin_amdgcn_s_sleep(1);
;     if ((++sp & 255u) == 0u) { if (xb_ld(&bar[XB_TMO])) break; if (sp > XB_SPIN_CAP) { atomicAdd(&bar[XB_TMO], 1u); break; } }
;   }
.LBB0_2025:
	global_load_dword v15, v16, s[44:45] offset:1024 sc1
	global_load_dword v0, v16, s[44:45] offset:1280 sc1
	global_load_dword v1, v16, s[44:45] offset:1536 sc1
	global_load_dword v2, v16, s[44:45] offset:1792 sc1
	global_load_dword v3, v16, s[44:45] offset:2048 sc1
	global_load_dword v4, v16, s[44:45] offset:2304 sc1
	global_load_dword v5, v16, s[44:45] offset:2560 sc1
	global_load_dword v6, v16, s[44:45] offset:2816 sc1
	global_load_dword v7, v16, s[44:45] offset:3072 sc1
	global_load_dword v8, v16, s[44:45] offset:3328 sc1
	global_load_dword v9, v16, s[44:45] offset:3584 sc1
	global_load_dword v10, v16, s[44:45] offset:3840 sc1
	global_load_dword v11, v16, s[0:1] sc1
	global_load_dword v12, v16, s[6:7] sc1
	global_load_dword v13, v16, s[8:9] sc1
	global_load_dword v14, v16, s[10:11] sc1
	s_mov_b64 s[12:13], -1
	s_mov_b64 s[14:15], -1
	s_waitcnt vmcnt(14)
	v_add_u32_e32 v17, v0, v15
	s_waitcnt vmcnt(13)
	v_add_u32_e32 v17, v17, v1
	s_waitcnt vmcnt(12)
	v_add_u32_e32 v17, v17, v2
	s_waitcnt vmcnt(11)
	v_add_u32_e32 v17, v17, v3
	s_waitcnt vmcnt(10)
	v_add_u32_e32 v17, v17, v4
	s_waitcnt vmcnt(9)
	v_add_u32_e32 v17, v17, v5
	s_waitcnt vmcnt(8)
	v_add_u32_e32 v17, v17, v6
	s_waitcnt vmcnt(7)
	v_add_u32_e32 v17, v17, v7
	s_waitcnt vmcnt(6)
	v_add_u32_e32 v17, v17, v8
	s_waitcnt vmcnt(5)
	v_add_u32_e32 v17, v17, v9
	s_waitcnt vmcnt(4)
	v_add_u32_e32 v17, v17, v10
	s_waitcnt vmcnt(3)
	v_add_u32_e32 v17, v17, v11
	s_waitcnt vmcnt(2)
	v_add_u32_e32 v17, v17, v12
	s_waitcnt vmcnt(1)
	v_add_u32_e32 v17, v17, v13
	s_waitcnt vmcnt(0)
	v_add_u32_e32 v17, v17, v14
	v_cmp_eq_u32_e32 vcc, s2, v17
	s_cbranch_vccnz .LBB0_2024
	s_and_b32 s12, s3, 0xff
	s_cmp_eq_u32 s12, 0
	s_mov_b64 s[12:13], -1
	s_mov_b64 s[16:17], -1
	s_sleep 3
	s_cbranch_scc0 .LBB0_2029
	global_load_dword v17, v16, s[44:45] offset:512 sc1
	s_waitcnt vmcnt(0)
	v_cmp_eq_u32_e32 vcc, 0, v17
	s_cbranch_vccnz .LBB0_2031
	s_mov_b64 s[16:17], 0

; DI unsigned xb_ld(unsigned* p) { return __hip_atomic_load(p, __ATOMIC_RELAXED, __HIP_MEMORY_SCOPE_AGENT); }
; DI unsigned xb_add(unsigned* p, unsigned v) { return __hip_atomic_fetch_add(p, v, __ATOMIC_RELAXED, __HIP_MEMORY_SCOPE_AGENT); }
; #define XB_SPIN(cond, bar) do { unsigned _sp = 0; while (cond) { __builtin_amdgcn_s_sleep(1); \
;     if ((++_sp & 255u) == 0u) { if (xb_ld(&(bar)[XB_TMO])) break; if (_sp > XB_SPIN_CAP) { atomicAdd(&(bar)[XB_TMO], 1u); break; } } } } while (0)
; DI void xcd_barrier(const XcdBarrier& b) {
;     ...
;       else XB_SPIN(xb_ld(&bar[XB_TOPGEN]) == tg, bar);
;       __builtin_amdgcn_fence(__ATOMIC_ACQUIRE, "agent");
;       xb_add(&bar[XB_XGEN(b.x)], 1u);
;       asm volatile("s_waitcnt vmcnt(0)" ::: "memory");
;     } else {
;       XB_SPIN(xb_ld(&bar[XB_XGEN(b.x)]) == gen, bar);
.LBB0_2043:
	s_and_b32 s3, s2, 0xff
	s_mov_b64 s[16:17], -1
	s_cmp_lg_u32 s3, 0
	s_mov_b64 s[20:21], -1
	s_sleep 3
	s_cbranch_scc1 .LBB0_2046
	global_load_dword v2, v0, s[44:45] offset:512 sc1
	s_waitcnt vmcnt(0)
	v_cmp_eq_u32_e32 vcc, 0, v2
	s_cbranch_vccnz .LBB0_2048
	s_mov_b64 s[20:21], 0
	s_mov_b64 s[18:19], -1

; DI unsigned xb_ld(unsigned* p) { return __hip_atomic_load(p, __ATOMIC_RELAXED, __HIP_MEMORY_SCOPE_AGENT); }
; DI unsigned xb_add(unsigned* p, unsigned v) { return __hip_atomic_fetch_add(p, v, __ATOMIC_RELAXED, __HIP_MEMORY_SCOPE_AGENT); }
; #define XB_SPIN(cond, bar) do { unsigned _sp = 0; while (cond) { __builtin_amdgcn_s_sleep(1); \
;     if ((++_sp & 255u) == 0u) { if (xb_ld(&(bar)[XB_TMO])) break; if (_sp > XB_SPIN_CAP) { atomicAdd(&(bar)[XB_TMO], 1u); break; } } } } while (0)
; DI void xcd_barrier(const XcdBarrier& b) {
;     ...
;       else XB_SPIN(xb_ld(&bar[XB_TOPGEN]) == tg, bar);
;       __builtin_amdgcn_fence(__ATOMIC_ACQUIRE, "agent");
;       xb_add(&bar[XB_XGEN(b.x)], 1u);
;       asm volatile("s_waitcnt vmcnt(0)" ::: "memory");
;     } else {
;       XB_SPIN(xb_ld(&bar[XB_XGEN(b.x)]) == gen, bar);
.LBB0_2060:
	s_and_b32 s3, s2, 0xff
	s_cmp_lg_u32 s3, 0
	s_mov_b64 s[20:21], -1
	s_sleep 3
	s_cbranch_scc1 .LBB0_2063
	global_load_dword v1, v0, s[10:11] sc1
	s_waitcnt vmcnt(0)
	v_cmp_eq_u32_e32 vcc, 0, v1
	s_cbranch_vccnz .LBB0_2065
	s_mov_b64 s[20:21], 0
	s_mov_b64 s[18:19], -1
